# first ks1 V-fragment reads hoisted into the MFMA->VALU pad of the row-max chain (fills s_nop), on top of best
# baseline (speedup 1.0000x reference)
; DI float ex2(float x) { return __builtin_amdgcn_exp2f(x); }
; DI float swap_max(float m) { auto rr = __builtin_amdgcn_permlane32_swap(__float_as_uint(m), __float_as_uint(m), false, false); return __builtin_fmaxf(__uint_as_float(rr[0]), __uint_as_float(rr[1])); }
; #define LOADV(dst, ks_) do { _Pragma("unroll") for (int dvb = 0; dvb < 4; ++dvb) { dst[2 * dvb] = vtr(vp + dvb * 4096 + (ks_) * 1024); dst[2 * dvb + 1] = vtr(vp + dvb * 4096 + (ks_) * 1024 + 512); } } while (0)
; #define MX3(a_, b_, c_) __builtin_fmaxf(__builtin_fmaxf((a_), (b_)), (c_))
; DI void attn_unit(const Params& p, int bh, int qb, char* lds, float lam, int tid, int lane, int wid, const bool build_tab) {
;     ...
;             float mxa = MX3(s0[0], s0[1], s1[0]), mxb = MX3(s0[2], s0[3], s1[1]); mxa = MX3(mxa, s1[2], s1[3]);
; #pragma unroll
;             for (int r = 4; r < 16; r += 4) { mxa = MX3(mxa, s0[r], s0[r + 1]); mxb = MX3(mxb, s0[r + 2], s0[r + 3]); mxa = MX3(mxa, s1[r], s1[r + 1]); mxb = MX3(mxb, s1[r + 2], s1[r + 3]); }
;             float mx = swap_max(__builtin_fmaxf(mxa, mxb));
;             const bool first = (t == 0);
;             if (first || __builtin_amdgcn_ballot_w64(mx > 8.0f) != 0ull) {
;                 const float dl = first ? mx : __builtin_fmaxf(mx, 0.f);
;                 const float f = first ? 1.0f : ex2(-dl);
;                 l *= f; nm -= dl;
; #pragma unroll
;                 for (int i = 0; i < 16; ++i) { o[0][i] *= f; o[1][i] *= f; o[2][i] *= f; o[3][i] *= f; cinit[i] = nm; s0[i] -= dl; s1[i] -= dl; }
;             }
;     ...
;             LOADV(vb, 1);
.LBB0_355:
	s_nop 1
	v_max_f32_e32 v221, v96, v97
	ds_read_b64_tr_b16 v[242:243], v220 offset:21504
	ds_read_b64_tr_b16 v[244:245], v220 offset:22016
	ds_read_b64_tr_b16 v[246:247], v220 offset:25600
	ds_read_b64_tr_b16 v[248:249], v220 offset:26112
	s_nop 3
	v_max3_f32 v222, v98, v99, v81
	v_max3_f32 v221, v221, v80, v82
	v_max3_f32 v221, v221, v83, v100
	v_max3_f32 v222, v222, v102, v103
	v_max3_f32 v221, v221, v101, v84
	v_max3_f32 v222, v222, v86, v87
	v_max3_f32 v221, v221, v85, v104
	v_max3_f32 v222, v222, v106, v107
	v_max3_f32 v221, v221, v105, v88
	v_max3_f32 v222, v222, v90, v91
	v_max3_f32 v221, v221, v89, v108
	v_max3_f32 v222, v222, v110, v111
	v_max3_f32 v221, v221, v109, v92
	v_max3_f32 v222, v222, v94, v95
	v_max3_f32 v221, v221, v93, v222
	v_mov_b32_e32 v222, v221
	s_nop 1
	v_permlane32_swap_b32_e32 v221, v222
	v_max_f32_e32 v221, v221, v222
	v_cmp_lt_f32_e32 vcc, s41, v221
	s_cbranch_vccz .LBB0_357
	v_max_f32_e32 v65, v221, v221
	v_max_f32_e32 v65, 0, v65
	v_exp_f32_e64 v66, -v65
	v_sub_f32_e32 v64, v64, v65
	v_sub_f32_e32 v111, v111, v65
	v_sub_f32_e32 v110, v110, v65
	v_pk_mul_f32 v[62:63], v[62:63], v[66:67] op_sel_hi:[1,0]
	v_pk_mul_f32 v[60:61], v[60:61], v[66:67] op_sel_hi:[1,0]
	v_pk_mul_f32 v[58:59], v[58:59], v[66:67] op_sel_hi:[1,0]
	v_pk_mul_f32 v[56:57], v[56:57], v[66:67] op_sel_hi:[1,0]
	v_pk_mul_f32 v[54:55], v[54:55], v[66:67] op_sel_hi:[1,0]
	v_pk_mul_f32 v[52:53], v[52:53], v[66:67] op_sel_hi:[1,0]
	v_pk_mul_f32 v[50:51], v[50:51], v[66:67] op_sel_hi:[1,0]
	v_pk_mul_f32 v[48:49], v[48:49], v[66:67] op_sel_hi:[1,0]
	v_pk_mul_f32 v[46:47], v[46:47], v[66:67] op_sel_hi:[1,0]
	v_pk_mul_f32 v[44:45], v[44:45], v[66:67] op_sel_hi:[1,0]
	v_pk_mul_f32 v[42:43], v[42:43], v[66:67] op_sel_hi:[1,0]
	v_pk_mul_f32 v[40:41], v[40:41], v[66:67] op_sel_hi:[1,0]
	v_pk_mul_f32 v[38:39], v[38:39], v[66:67] op_sel_hi:[1,0]
	v_pk_mul_f32 v[36:37], v[36:37], v[66:67] op_sel_hi:[1,0]
	v_pk_mul_f32 v[34:35], v[34:35], v[66:67] op_sel_hi:[1,0]
	v_pk_mul_f32 v[32:33], v[32:33], v[66:67] op_sel_hi:[1,0]
	v_pk_mul_f32 v[30:31], v[30:31], v[66:67] op_sel_hi:[1,0]
	v_pk_mul_f32 v[28:29], v[28:29], v[66:67] op_sel_hi:[1,0]
	v_pk_mul_f32 v[26:27], v[26:27], v[66:67] op_sel_hi:[1,0]
	v_pk_mul_f32 v[24:25], v[24:25], v[66:67] op_sel_hi:[1,0]
	v_pk_mul_f32 v[22:23], v[22:23], v[66:67] op_sel_hi:[1,0]
	v_pk_mul_f32 v[20:21], v[20:21], v[66:67] op_sel_hi:[1,0]
	v_pk_mul_f32 v[18:19], v[18:19], v[66:67] op_sel_hi:[1,0]
	v_pk_mul_f32 v[16:17], v[16:17], v[66:67] op_sel_hi:[1,0]
	v_pk_mul_f32 v[14:15], v[14:15], v[66:67] op_sel_hi:[1,0]
	v_pk_mul_f32 v[12:13], v[12:13], v[66:67] op_sel_hi:[1,0]
	v_pk_mul_f32 v[10:11], v[10:11], v[66:67] op_sel_hi:[1,0]
	v_pk_mul_f32 v[8:9], v[8:9], v[66:67] op_sel_hi:[1,0]
	v_pk_mul_f32 v[6:7], v[6:7], v[66:67] op_sel_hi:[1,0]
	v_pk_mul_f32 v[4:5], v[4:5], v[66:67] op_sel_hi:[1,0]
	v_pk_mul_f32 v[2:3], v[2:3], v[66:67] op_sel_hi:[1,0]
	v_pk_mul_f32 v[0:1], v[0:1], v[66:67] op_sel_hi:[1,0]
	v_sub_f32_e32 v109, v109, v65
	v_sub_f32_e32 v108, v108, v65
	v_sub_f32_e32 v107, v107, v65
	v_sub_f32_e32 v106, v106, v65
	v_sub_f32_e32 v105, v105, v65
	v_sub_f32_e32 v104, v104, v65
	v_sub_f32_e32 v103, v103, v65
	v_sub_f32_e32 v102, v102, v65
	v_sub_f32_e32 v101, v101, v65
	v_sub_f32_e32 v100, v100, v65
	v_sub_f32_e32 v99, v99, v65
	v_sub_f32_e32 v98, v98, v65
	v_sub_f32_e32 v97, v97, v65
	v_sub_f32_e32 v96, v96, v65
	v_sub_f32_e32 v95, v95, v65
	v_sub_f32_e32 v94, v94, v65
	v_sub_f32_e32 v93, v93, v65
	v_sub_f32_e32 v92, v92, v65
	v_sub_f32_e32 v91, v91, v65
	v_sub_f32_e32 v90, v90, v65
	v_sub_f32_e32 v89, v89, v65
	v_sub_f32_e32 v88, v88, v65
	v_sub_f32_e32 v87, v87, v65
	v_sub_f32_e32 v86, v86, v65
	v_sub_f32_e32 v85, v85, v65
	v_sub_f32_e32 v84, v84, v65
	v_sub_f32_e32 v83, v83, v65
	v_sub_f32_e32 v82, v82, v65
	v_sub_f32_e32 v81, v81, v65
	v_sub_f32_e32 v80, v80, v65
	v_mul_f32_e32 v146, v146, v66
	v_mov_b32_e32 v65, v64
	v_mov_b32_e32 v66, v64
	v_mov_b32_e32 v67, v64
	v_mov_b32_e32 v68, v64
	v_mov_b32_e32 v69, v64
	v_mov_b32_e32 v70, v64
	v_mov_b32_e32 v71, v64
	v_mov_b32_e32 v72, v64
	v_mov_b32_e32 v73, v64
	v_mov_b32_e32 v74, v64
	v_mov_b32_e32 v75, v64
	v_mov_b32_e32 v76, v64
	v_mov_b32_e32 v77, v64
	v_mov_b32_e32 v78, v64
	v_mov_b32_e32 v79, v64

; #define LOADV(dst, ks_) do { _Pragma("unroll") for (int dvb = 0; dvb < 4; ++dvb) { dst[2 * dvb] = vtr(vp + dvb * 4096 + (ks_) * 1024); dst[2 * dvb + 1] = vtr(vp + dvb * 4096 + (ks_) * 1024 + 512); } } while (0)
; #define MF4(src, pfrag) do { _Pragma("unroll") for (int dvb = 0; dvb < 4; ++dvb) { \
;         const bf16x8 vf_ = __builtin_shufflevector(src[2 * dvb], src[2 * dvb + 1], 0, 1, 2, 3, 4, 5, 6, 7); o[dvb] = MFMA32(vf_, pfrag, o[dvb]); } } while (0)
; #define EXPQ(S, lo_, RS, PF) do { _Pragma("unroll") for (int i = lo_; i < lo_ + 8; ++i) { S[i] = ex2(S[i]); RS += S[i]; } \
;               u32x4 w_; w_.x = pk2(S[lo_], S[lo_ + 1]); w_.y = pk2(S[lo_ + 2], S[lo_ + 3]); w_.z = pk2(S[lo_ + 4], S[lo_ + 5]); w_.w = pk2(S[lo_ + 6], S[lo_ + 7]); PF = __builtin_bit_cast(bf16x8, w_); } while (0)
; DI void attn_unit(const Params& p, int bh, int qb, char* lds, float lam, int tid, int lane, int wid, const bool build_tab) {
;     ...
;             float rs0 = 0.f, rs1 = 0.f;
;     ...
;             EXPQ(s0, 0, rs0, pf[0]);
;             LOADV(vb, 1);
;             MF4(va, pf[0]);
;             EXPQ(s0, 8, rs1, pf[1]);
;             LOADV(va, 2);
;             MF4(vb, pf[1]);
;             EXPQ(s1, 0, rs0, pf[2]);
;             LOADV(vb, 3);
;             MF4(va, pf[2]);
;             EXPQ(s1, 8, rs1, pf[3]);
;             MF4(vb, pf[3]);
;             l += rs0 + rs1;
.LBB0_359:
	v_exp_f32_e32 v222, v96
	v_exp_f32_e32 v224, v97
	v_exp_f32_e32 v226, v98
	v_exp_f32_e32 v228, v99
	v_exp_f32_e32 v230, v100
	v_exp_f32_e32 v232, v101
	v_exp_f32_e32 v234, v102
	v_exp_f32_e32 v236, v103
	v_cvt_pk_bf16_f32 v96, v222, v224
	v_cvt_pk_bf16_f32 v97, v226, v228
	v_cvt_pk_bf16_f32 v98, v230, v232
	v_cvt_pk_bf16_f32 v99, v234, v236
	ds_read_b64_tr_b16 v[100:101], v220 offset:17408
	ds_read_b64_tr_b16 v[102:103], v220 offset:17920
	s_waitcnt lgkmcnt(12)
	v_mfma_f32_32x32x16_bf16 v[48:63], v[140:143], v[96:99], v[48:63]
	ds_read_b64_tr_b16 v[250:251], v220 offset:29696
	ds_read_b64_tr_b16 v[252:253], v220 offset:30208
	v_exp_f32_e32 v223, v104
	v_exp_f32_e32 v225, v105
	v_exp_f32_e32 v227, v106
	v_add_f32_e32 v221, v224, v222
	s_waitcnt lgkmcnt(12)
	v_mfma_f32_32x32x16_bf16 v[32:47], v[136:139], v[96:99], v[32:47]
	v_exp_f32_e32 v229, v107
	v_exp_f32_e32 v231, v108
	v_exp_f32_e32 v233, v109
	v_add_f32_e32 v221, v226, v221
	s_waitcnt lgkmcnt(10)
	v_mfma_f32_32x32x16_bf16 v[16:31], v[132:135], v[96:99], v[16:31]
	v_exp_f32_e32 v235, v110
	v_exp_f32_e32 v237, v111
	v_add_f32_e32 v221, v228, v221
	v_add_f32_e32 v221, v230, v221
	ds_read_b64_tr_b16 v[104:105], v220 offset:18432
	ds_read_b64_tr_b16 v[106:107], v220 offset:18944
	ds_read_b64_tr_b16 v[108:109], v220 offset:19456
	ds_read_b64_tr_b16 v[110:111], v220 offset:19968
	s_waitcnt lgkmcnt(12)
	v_mfma_f32_32x32x16_bf16 v[0:15], v[128:131], v[96:99], v[0:15]
	ds_read_b64_tr_b16 v[128:129], v220 offset:26624
	ds_read_b64_tr_b16 v[130:131], v220 offset:27136
	v_cvt_pk_bf16_f32 v96, v223, v225
	v_cvt_pk_bf16_f32 v97, v227, v229
	v_cvt_pk_bf16_f32 v98, v231, v233
	v_cvt_pk_bf16_f32 v99, v235, v237
	v_exp_f32_e32 v140, v84
	v_exp_f32_e32 v142, v85
	s_waitcnt lgkmcnt(8)
	v_mfma_f32_32x32x16_bf16 v[48:63], v[100:103], v[96:99], v[48:63]
	v_exp_f32_e32 v238, v86
	v_exp_f32_e32 v240, v87
	v_add_f32_e32 v221, v232, v221
	ds_read_b64_tr_b16 v[84:85], v220 offset:22528
	ds_read_b64_tr_b16 v[86:87], v220 offset:23040
	v_exp_f32_e32 v136, v82
	s_waitcnt lgkmcnt(14)
	v_mfma_f32_32x32x16_bf16 v[32:47], v[242:245], v[96:99], v[32:47]
	ds_read_b64_tr_b16 v[242:243], v220 offset:23552
	ds_read_b64_tr_b16 v[244:245], v220 offset:24064
	v_exp_f32_e32 v138, v83
	v_exp_f32_e32 v132, v80
	v_exp_f32_e32 v134, v81
	v_add_f32_e32 v221, v234, v221
	s_waitcnt lgkmcnt(14)
	v_mfma_f32_32x32x16_bf16 v[16:31], v[246:249], v[96:99], v[16:31]
	ds_read_b64_tr_b16 v[246:247], v220 offset:27648
	ds_read_b64_tr_b16 v[248:249], v220 offset:28160
	v_cvt_pk_bf16_f32 v80, v132, v134
	v_cvt_pk_bf16_f32 v81, v136, v138
	v_cvt_pk_bf16_f32 v82, v140, v142
	v_cvt_pk_bf16_f32 v83, v238, v240
	v_exp_f32_e32 v133, v88
	v_exp_f32_e32 v135, v89
	s_waitcnt lgkmcnt(12)
	v_mfma_f32_32x32x16_bf16 v[0:15], v[250:253], v[96:99], v[0:15]
	ds_read_b64_tr_b16 v[250:251], v220 offset:31744
	ds_read_b64_tr_b16 v[252:253], v220 offset:32256
	v_exp_f32_e32 v137, v90
	v_exp_f32_e32 v139, v91
	v_add_f32_e32 v221, v236, v221
	ds_read_b64_tr_b16 v[88:89], v220 offset:30720
	ds_read_b64_tr_b16 v[90:91], v220 offset:31232
	v_exp_f32_e32 v141, v92
	s_waitcnt lgkmcnt(14)
	v_mfma_f32_32x32x16_bf16 v[48:63], v[104:107], v[80:83], v[48:63]
	v_exp_f32_e32 v143, v93
	v_exp_f32_e32 v239, v94
	v_exp_f32_e32 v241, v95
	v_add_f32_e32 v221, v132, v221
	s_waitcnt lgkmcnt(8)
	v_mfma_f32_32x32x16_bf16 v[32:47], v[84:87], v[80:83], v[32:47]
	v_add_f32_e32 v93, v225, v223
	v_add_f32_e32 v221, v134, v221
	v_add_f32_e32 v93, v227, v93
	v_add_f32_e32 v221, v136, v221
	v_add_f32_e32 v93, v229, v93
	v_add_f32_e32 v221, v138, v221
	s_waitcnt lgkmcnt(10)
	v_mfma_f32_32x32x16_bf16 v[16:31], v[128:131], v[80:83], v[16:31]
	v_add_f32_e32 v93, v231, v93
	v_add_f32_e32 v221, v140, v221
	v_add_f32_e32 v93, v233, v93
	v_add_f32_e32 v221, v142, v221
	v_add_f32_e32 v93, v235, v93
	v_add_f32_e32 v221, v238, v221
	v_add_f32_e32 v93, v237, v93
	s_waitcnt lgkmcnt(0)
	v_mfma_f32_32x32x16_bf16 v[0:15], v[88:91], v[80:83], v[0:15]
	v_cvt_pk_bf16_f32 v80, v133, v135
	v_cvt_pk_bf16_f32 v81, v137, v139
	v_cvt_pk_bf16_f32 v82, v141, v143
	v_cvt_pk_bf16_f32 v83, v239, v241
	v_add_f32_e32 v221, v240, v221
	v_add_f32_e32 v93, v133, v93
	s_waitcnt lgkmcnt(12)
	v_mfma_f32_32x32x16_bf16 v[48:63], v[108:111], v[80:83], v[48:63]
	v_add_f32_e32 v93, v135, v93
	v_add_f32_e32 v93, v137, v93
	s_waitcnt lgkmcnt(6)
	v_mfma_f32_32x32x16_bf16 v[32:47], v[242:245], v[80:83], v[32:47]
	v_add_f32_e32 v93, v139, v93
	v_add_f32_e32 v93, v141, v93
	s_waitcnt lgkmcnt(4)
	v_mfma_f32_32x32x16_bf16 v[16:31], v[246:249], v[80:83], v[16:31]
	v_add_f32_e32 v93, v143, v93
	v_add_f32_e32 v93, v239, v93
	s_waitcnt lgkmcnt(2)
	v_mfma_f32_32x32x16_bf16 v[0:15], v[250:253], v[80:83], v[0:15]
	v_add_f32_e32 v93, v241, v93
	v_add_f32_e32 v221, v221, v93
	v_add_f32_e32 v146, v146, v221

; DI float ex2(float x) { return __builtin_amdgcn_exp2f(x); }
; DI float swap_max(float m) { auto rr = __builtin_amdgcn_permlane32_swap(__float_as_uint(m), __float_as_uint(m), false, false); return __builtin_fmaxf(__uint_as_float(rr[0]), __uint_as_float(rr[1])); }
; #define LOADV(dst, ks_) do { _Pragma("unroll") for (int dvb = 0; dvb < 4; ++dvb) { dst[2 * dvb] = vtr(vp + dvb * 4096 + (ks_) * 1024); dst[2 * dvb + 1] = vtr(vp + dvb * 4096 + (ks_) * 1024 + 512); } } while (0)
; #define MX3(a_, b_, c_) __builtin_fmaxf(__builtin_fmaxf((a_), (b_)), (c_))
; DI void attn_unit(const Params& p, int bh, int qb, char* lds, float lam, int tid, int lane, int wid, const bool build_tab) {
;     ...
;             float mxa = MX3(s0[0], s0[1], s1[0]), mxb = MX3(s0[2], s0[3], s1[1]); mxa = MX3(mxa, s1[2], s1[3]);
; #pragma unroll
;             for (int r = 4; r < 16; r += 4) { mxa = MX3(mxa, s0[r], s0[r + 1]); mxb = MX3(mxb, s0[r + 2], s0[r + 3]); mxa = MX3(mxa, s1[r], s1[r + 1]); mxb = MX3(mxb, s1[r + 2], s1[r + 3]); }
;             float mx = swap_max(__builtin_fmaxf(mxa, mxb));
;             const bool first = (t == 0);
;             if (first || __builtin_amdgcn_ballot_w64(mx > 8.0f) != 0ull) {
;                 const float dl = first ? mx : __builtin_fmaxf(mx, 0.f);
;                 const float f = first ? 1.0f : ex2(-dl);
;                 l *= f; nm -= dl;
; #pragma unroll
;                 for (int i = 0; i < 16; ++i) { o[0][i] *= f; o[1][i] *= f; o[2][i] *= f; o[3][i] *= f; cinit[i] = nm; s0[i] -= dl; s1[i] -= dl; }
;             }
;     ...
;             LOADV(vb, 1);
.LBB0_375:
	s_nop 1
	v_max_f32_e32 v178, v96, v97
	ds_read_b64_tr_b16 v[230:231], v177 offset:21504
	ds_read_b64_tr_b16 v[232:233], v177 offset:22016
	ds_read_b64_tr_b16 v[234:235], v177 offset:25600
	ds_read_b64_tr_b16 v[236:237], v177 offset:26112
	s_nop 3
	v_max3_f32 v179, v98, v99, v81
	v_max3_f32 v178, v178, v80, v82
	v_max3_f32 v178, v178, v83, v100
	v_max3_f32 v179, v179, v102, v103
	v_max3_f32 v178, v178, v101, v84
	v_max3_f32 v179, v179, v86, v87
	v_max3_f32 v178, v178, v85, v104
	v_max3_f32 v179, v179, v106, v107
	v_max3_f32 v178, v178, v105, v88
	v_max3_f32 v179, v179, v90, v91
	v_max3_f32 v178, v178, v89, v108
	v_max3_f32 v179, v179, v110, v111
	v_max3_f32 v178, v178, v109, v92
	v_max3_f32 v179, v179, v94, v95
	v_max3_f32 v178, v178, v93, v179
	v_mov_b32_e32 v179, v178
	s_nop 1
	v_permlane32_swap_b32_e32 v178, v179
	v_max_f32_e32 v178, v178, v179
	v_cmp_lt_f32_e32 vcc, s41, v178
	s_cbranch_vccz .LBB0_377
	v_max_f32_e32 v65, v178, v178
	v_max_f32_e32 v65, 0, v65
	v_exp_f32_e64 v66, -v65
	v_sub_f32_e32 v64, v64, v65
	v_sub_f32_e32 v111, v111, v65
	v_sub_f32_e32 v110, v110, v65
	v_pk_mul_f32 v[62:63], v[62:63], v[66:67] op_sel_hi:[1,0]
	v_pk_mul_f32 v[60:61], v[60:61], v[66:67] op_sel_hi:[1,0]
	v_pk_mul_f32 v[58:59], v[58:59], v[66:67] op_sel_hi:[1,0]
	v_pk_mul_f32 v[56:57], v[56:57], v[66:67] op_sel_hi:[1,0]
	v_pk_mul_f32 v[54:55], v[54:55], v[66:67] op_sel_hi:[1,0]
	v_pk_mul_f32 v[52:53], v[52:53], v[66:67] op_sel_hi:[1,0]
	v_pk_mul_f32 v[50:51], v[50:51], v[66:67] op_sel_hi:[1,0]
	v_pk_mul_f32 v[48:49], v[48:49], v[66:67] op_sel_hi:[1,0]
	v_pk_mul_f32 v[46:47], v[46:47], v[66:67] op_sel_hi:[1,0]
	v_pk_mul_f32 v[44:45], v[44:45], v[66:67] op_sel_hi:[1,0]
	v_pk_mul_f32 v[42:43], v[42:43], v[66:67] op_sel_hi:[1,0]
	v_pk_mul_f32 v[40:41], v[40:41], v[66:67] op_sel_hi:[1,0]
	v_pk_mul_f32 v[38:39], v[38:39], v[66:67] op_sel_hi:[1,0]
	v_pk_mul_f32 v[36:37], v[36:37], v[66:67] op_sel_hi:[1,0]
	v_pk_mul_f32 v[34:35], v[34:35], v[66:67] op_sel_hi:[1,0]
	v_pk_mul_f32 v[32:33], v[32:33], v[66:67] op_sel_hi:[1,0]
	v_pk_mul_f32 v[30:31], v[30:31], v[66:67] op_sel_hi:[1,0]
	v_pk_mul_f32 v[28:29], v[28:29], v[66:67] op_sel_hi:[1,0]
	v_pk_mul_f32 v[26:27], v[26:27], v[66:67] op_sel_hi:[1,0]
	v_pk_mul_f32 v[24:25], v[24:25], v[66:67] op_sel_hi:[1,0]
	v_pk_mul_f32 v[22:23], v[22:23], v[66:67] op_sel_hi:[1,0]
	v_pk_mul_f32 v[20:21], v[20:21], v[66:67] op_sel_hi:[1,0]
	v_pk_mul_f32 v[18:19], v[18:19], v[66:67] op_sel_hi:[1,0]
	v_pk_mul_f32 v[16:17], v[16:17], v[66:67] op_sel_hi:[1,0]
	v_pk_mul_f32 v[14:15], v[14:15], v[66:67] op_sel_hi:[1,0]
	v_pk_mul_f32 v[12:13], v[12:13], v[66:67] op_sel_hi:[1,0]
	v_pk_mul_f32 v[10:11], v[10:11], v[66:67] op_sel_hi:[1,0]
	v_pk_mul_f32 v[8:9], v[8:9], v[66:67] op_sel_hi:[1,0]
	v_pk_mul_f32 v[6:7], v[6:7], v[66:67] op_sel_hi:[1,0]
	v_pk_mul_f32 v[4:5], v[4:5], v[66:67] op_sel_hi:[1,0]
	v_pk_mul_f32 v[2:3], v[2:3], v[66:67] op_sel_hi:[1,0]
	v_pk_mul_f32 v[0:1], v[0:1], v[66:67] op_sel_hi:[1,0]
	v_sub_f32_e32 v109, v109, v65
	v_sub_f32_e32 v108, v108, v65
	v_sub_f32_e32 v107, v107, v65
	v_sub_f32_e32 v106, v106, v65
	v_sub_f32_e32 v105, v105, v65
	v_sub_f32_e32 v104, v104, v65
	v_sub_f32_e32 v103, v103, v65
	v_sub_f32_e32 v102, v102, v65
	v_sub_f32_e32 v101, v101, v65
	v_sub_f32_e32 v100, v100, v65
	v_sub_f32_e32 v99, v99, v65
	v_sub_f32_e32 v98, v98, v65
	v_sub_f32_e32 v97, v97, v65
	v_sub_f32_e32 v96, v96, v65
	v_sub_f32_e32 v95, v95, v65
	v_sub_f32_e32 v94, v94, v65
	v_sub_f32_e32 v93, v93, v65
	v_sub_f32_e32 v92, v92, v65
	v_sub_f32_e32 v91, v91, v65
	v_sub_f32_e32 v90, v90, v65
	v_sub_f32_e32 v89, v89, v65
	v_sub_f32_e32 v88, v88, v65
	v_sub_f32_e32 v87, v87, v65
	v_sub_f32_e32 v86, v86, v65
	v_sub_f32_e32 v85, v85, v65
	v_sub_f32_e32 v84, v84, v65
	v_sub_f32_e32 v83, v83, v65
	v_sub_f32_e32 v82, v82, v65
	v_sub_f32_e32 v81, v81, v65
	v_sub_f32_e32 v80, v80, v65
	v_mul_f32_e32 v176, v176, v66
	v_mov_b32_e32 v65, v64
	v_mov_b32_e32 v66, v64
	v_mov_b32_e32 v67, v64
	v_mov_b32_e32 v68, v64
	v_mov_b32_e32 v69, v64
	v_mov_b32_e32 v70, v64
	v_mov_b32_e32 v71, v64
	v_mov_b32_e32 v72, v64
	v_mov_b32_e32 v73, v64
	v_mov_b32_e32 v74, v64
	v_mov_b32_e32 v75, v64
	v_mov_b32_e32 v76, v64
	v_mov_b32_e32 v77, v64
	v_mov_b32_e32 v78, v64
	v_mov_b32_e32 v79, v64

; #define LOADV(dst, ks_) do { _Pragma("unroll") for (int dvb = 0; dvb < 4; ++dvb) { dst[2 * dvb] = vtr(vp + dvb * 4096 + (ks_) * 1024); dst[2 * dvb + 1] = vtr(vp + dvb * 4096 + (ks_) * 1024 + 512); } } while (0)
; #define MF4(src, pfrag) do { _Pragma("unroll") for (int dvb = 0; dvb < 4; ++dvb) { \
;         const bf16x8 vf_ = __builtin_shufflevector(src[2 * dvb], src[2 * dvb + 1], 0, 1, 2, 3, 4, 5, 6, 7); o[dvb] = MFMA32(vf_, pfrag, o[dvb]); } } while (0)
; #define EXPQ(S, lo_, RS, PF) do { _Pragma("unroll") for (int i = lo_; i < lo_ + 8; ++i) { S[i] = ex2(S[i]); RS += S[i]; } \
;               u32x4 w_; w_.x = pk2(S[lo_], S[lo_ + 1]); w_.y = pk2(S[lo_ + 2], S[lo_ + 3]); w_.z = pk2(S[lo_ + 4], S[lo_ + 5]); w_.w = pk2(S[lo_ + 6], S[lo_ + 7]); PF = __builtin_bit_cast(bf16x8, w_); } while (0)
; DI void attn_unit(const Params& p, int bh, int qb, char* lds, float lam, int tid, int lane, int wid, const bool build_tab) {
;     ...
;             float rs0 = 0.f, rs1 = 0.f;
;     ...
;             EXPQ(s0, 0, rs0, pf[0]);
;             LOADV(vb, 1);
;             MF4(va, pf[0]);
;             EXPQ(s0, 8, rs1, pf[1]);
;             LOADV(va, 2);
;             MF4(vb, pf[1]);
;             EXPQ(s1, 0, rs0, pf[2]);
;             LOADV(vb, 3);
;             MF4(va, pf[2]);
;             EXPQ(s1, 8, rs1, pf[3]);
;             MF4(vb, pf[3]);
;             l += rs0 + rs1;
.LBB0_379:
	v_exp_f32_e32 v178, v96
	v_exp_f32_e32 v180, v97
	v_exp_f32_e32 v182, v98
	v_exp_f32_e32 v184, v99
	v_exp_f32_e32 v186, v100
	v_exp_f32_e32 v188, v101
	v_exp_f32_e32 v190, v102
	v_exp_f32_e32 v192, v103
	v_cvt_pk_bf16_f32 v96, v178, v180
	v_cvt_pk_bf16_f32 v97, v182, v184
	v_cvt_pk_bf16_f32 v98, v186, v188
	v_cvt_pk_bf16_f32 v99, v190, v192
	ds_read_b64_tr_b16 v[100:101], v177 offset:17408
	ds_read_b64_tr_b16 v[102:103], v177 offset:17920
	s_waitcnt lgkmcnt(12)
	v_mfma_f32_32x32x16_bf16 v[48:63], v[140:143], v[96:99], v[48:63]
	ds_read_b64_tr_b16 v[238:239], v177 offset:29696
	ds_read_b64_tr_b16 v[240:241], v177 offset:30208
	v_exp_f32_e32 v179, v104
	v_exp_f32_e32 v181, v105
	v_exp_f32_e32 v183, v106
	v_add_f32_e32 v242, v180, v178
	s_waitcnt lgkmcnt(12)
	v_mfma_f32_32x32x16_bf16 v[32:47], v[136:139], v[96:99], v[32:47]
	v_exp_f32_e32 v185, v107
	v_exp_f32_e32 v187, v108
	v_exp_f32_e32 v189, v109
	v_add_f32_e32 v242, v182, v242
	s_waitcnt lgkmcnt(10)
	v_mfma_f32_32x32x16_bf16 v[16:31], v[132:135], v[96:99], v[16:31]
	v_exp_f32_e32 v191, v110
	v_exp_f32_e32 v193, v111
	v_add_f32_e32 v242, v184, v242
	v_add_f32_e32 v242, v186, v242
	ds_read_b64_tr_b16 v[104:105], v177 offset:18432
	ds_read_b64_tr_b16 v[106:107], v177 offset:18944
	ds_read_b64_tr_b16 v[108:109], v177 offset:19456
	ds_read_b64_tr_b16 v[110:111], v177 offset:19968
	s_waitcnt lgkmcnt(12)
	v_mfma_f32_32x32x16_bf16 v[0:15], v[128:131], v[96:99], v[0:15]
	ds_read_b64_tr_b16 v[128:129], v177 offset:26624
	ds_read_b64_tr_b16 v[130:131], v177 offset:27136
	v_cvt_pk_bf16_f32 v96, v179, v181
	v_cvt_pk_bf16_f32 v97, v183, v185
	v_cvt_pk_bf16_f32 v98, v187, v189
	v_cvt_pk_bf16_f32 v99, v191, v193
	v_exp_f32_e32 v140, v84
	v_exp_f32_e32 v142, v85
	s_waitcnt lgkmcnt(8)
	v_mfma_f32_32x32x16_bf16 v[48:63], v[100:103], v[96:99], v[48:63]
	v_exp_f32_e32 v194, v86
	v_exp_f32_e32 v196, v87
	v_add_f32_e32 v242, v188, v242
	ds_read_b64_tr_b16 v[84:85], v177 offset:22528
	ds_read_b64_tr_b16 v[86:87], v177 offset:23040
	v_exp_f32_e32 v136, v82
	s_waitcnt lgkmcnt(14)
	v_mfma_f32_32x32x16_bf16 v[32:47], v[230:233], v[96:99], v[32:47]
	ds_read_b64_tr_b16 v[230:231], v177 offset:23552
	ds_read_b64_tr_b16 v[232:233], v177 offset:24064
	v_exp_f32_e32 v138, v83
	v_exp_f32_e32 v132, v80
	v_exp_f32_e32 v134, v81
	v_add_f32_e32 v242, v190, v242
	s_waitcnt lgkmcnt(14)
	v_mfma_f32_32x32x16_bf16 v[16:31], v[234:237], v[96:99], v[16:31]
	ds_read_b64_tr_b16 v[234:235], v177 offset:27648
	ds_read_b64_tr_b16 v[236:237], v177 offset:28160
	v_cvt_pk_bf16_f32 v80, v132, v134
	v_cvt_pk_bf16_f32 v81, v136, v138
	v_cvt_pk_bf16_f32 v82, v140, v142
	v_cvt_pk_bf16_f32 v83, v194, v196
	v_exp_f32_e32 v133, v88
	v_exp_f32_e32 v135, v89
	s_waitcnt lgkmcnt(12)
	v_mfma_f32_32x32x16_bf16 v[0:15], v[238:241], v[96:99], v[0:15]
	ds_read_b64_tr_b16 v[238:239], v177 offset:31744
	ds_read_b64_tr_b16 v[240:241], v177 offset:32256
	v_exp_f32_e32 v137, v90
	v_exp_f32_e32 v139, v91
	v_add_f32_e32 v242, v192, v242
	ds_read_b64_tr_b16 v[88:89], v177 offset:30720
	ds_read_b64_tr_b16 v[90:91], v177 offset:31232
	v_exp_f32_e32 v141, v92
	s_waitcnt lgkmcnt(14)
	v_mfma_f32_32x32x16_bf16 v[48:63], v[104:107], v[80:83], v[48:63]
	v_exp_f32_e32 v143, v93
	v_exp_f32_e32 v195, v94
	v_exp_f32_e32 v197, v95
	v_add_f32_e32 v242, v132, v242
	s_waitcnt lgkmcnt(8)
	v_mfma_f32_32x32x16_bf16 v[32:47], v[84:87], v[80:83], v[32:47]
	v_add_f32_e32 v243, v181, v179
	v_add_f32_e32 v242, v134, v242
	v_add_f32_e32 v243, v183, v243
	v_add_f32_e32 v242, v136, v242
	v_add_f32_e32 v243, v185, v243
	v_add_f32_e32 v242, v138, v242
	s_waitcnt lgkmcnt(10)
	v_mfma_f32_32x32x16_bf16 v[16:31], v[128:131], v[80:83], v[16:31]
	v_add_f32_e32 v243, v187, v243
	v_add_f32_e32 v242, v140, v242
	v_add_f32_e32 v243, v189, v243
	v_add_f32_e32 v242, v142, v242
	v_add_f32_e32 v243, v191, v243
	v_add_f32_e32 v242, v194, v242
	v_add_f32_e32 v243, v193, v243
	s_waitcnt lgkmcnt(0)
	v_mfma_f32_32x32x16_bf16 v[0:15], v[88:91], v[80:83], v[0:15]
	v_cvt_pk_bf16_f32 v80, v133, v135
	v_cvt_pk_bf16_f32 v81, v137, v139
	v_cvt_pk_bf16_f32 v82, v141, v143
	v_cvt_pk_bf16_f32 v83, v195, v197
	v_add_f32_e32 v242, v196, v242
	v_add_f32_e32 v243, v133, v243
	s_waitcnt lgkmcnt(12)
	v_mfma_f32_32x32x16_bf16 v[48:63], v[108:111], v[80:83], v[48:63]
	v_add_f32_e32 v243, v135, v243
	v_add_f32_e32 v243, v137, v243
	s_waitcnt lgkmcnt(6)
	v_mfma_f32_32x32x16_bf16 v[32:47], v[230:233], v[80:83], v[32:47]
	v_add_f32_e32 v243, v139, v243
	v_add_f32_e32 v243, v141, v243
	s_waitcnt lgkmcnt(4)
	v_mfma_f32_32x32x16_bf16 v[16:31], v[234:237], v[80:83], v[16:31]
	v_add_f32_e32 v243, v143, v243
	v_add_f32_e32 v243, v195, v243
	s_waitcnt lgkmcnt(2)
	v_mfma_f32_32x32x16_bf16 v[0:15], v[238:241], v[80:83], v[0:15]
	v_add_f32_e32 v243, v197, v243
	v_add_f32_e32 v242, v242, v243
	v_add_f32_e32 v176, v176, v242
